# attention loop: drop 2 NaN-canonicalizing v_max and 1 copy per tile (on top of C-operand -mhat fold and LDS prefetch swap)
# speedup vs baseline: 1.0039x; 1.0039x over previous
.LBB0_842:
	s_lshl_b32 s0, s36, 1
	v_add_u32_e32 v200, s0, v211
	s_setprio 1
	ds_read_b64_tr_b16 v[196:197], v200 offset:24576
	ds_read_b64_tr_b16 v[198:199], v200 offset:25088
	v_add_f32_e32 v100, v80, v81
	v_add_f32_e32 v100, v82, v100
	v_add_f32_e32 v100, v83, v100
	v_add_f32_e32 v100, v84, v100
	v_add_f32_e32 v116, v85, v100
	s_waitcnt lgkmcnt(9)
	v_mfma_f32_32x32x16_bf16 v[96:111], v[96:99], v[156:159], v[236:251]
	v_cvt_pk_bf16_f32 v140, v80, v81
	v_cvt_pk_bf16_f32 v141, v82, v83
	ds_read_b64_tr_b16 v[188:189], v200 offset:28672
	ds_read_b64_tr_b16 v[190:191], v200 offset:29184
	v_add_f32_e32 v80, v86, v116
	v_add_f32_e32 v80, v87, v80
	v_add_f32_e32 v80, v88, v80
	v_add_f32_e32 v80, v89, v80
	v_cvt_pk_bf16_f32 v142, v84, v85
	v_cvt_pk_bf16_f32 v143, v86, v87
	s_waitcnt lgkmcnt(10)
	v_mfma_f32_32x32x16_bf16 v[112:127], v[112:115], v[156:159], v[236:251]
	ds_read_b64_tr_b16 v[184:185], v200 offset:25600
	ds_read_b64_tr_b16 v[186:187], v200 offset:26112
	s_waitcnt lgkmcnt(11)
	v_mfma_f32_32x32x16_bf16 v[96:111], v[180:183], v[152:155], v[96:111]
	v_add_f32_e32 v80, v90, v80
	v_add_f32_e32 v80, v91, v80
	v_add_f32_e32 v80, v92, v80
	v_add_f32_e32 v80, v93, v80
	v_cvt_pk_bf16_f32 v136, v88, v89
	v_cvt_pk_bf16_f32 v137, v90, v91
	ds_read_b64_tr_b16 v[180:181], v200 offset:29696
	ds_read_b64_tr_b16 v[182:183], v200 offset:30208
	v_add_f32_e32 v80, v94, v80
	v_add_f32_e32 v80, v95, v80
	v_add_f32_e32 v80, v64, v80
	v_add_f32_e32 v80, v65, v80
	v_cvt_pk_bf16_f32 v138, v92, v93
	v_cvt_pk_bf16_f32 v139, v94, v95
	s_waitcnt lgkmcnt(12)
	v_mfma_f32_32x32x16_bf16 v[112:127], v[176:179], v[152:155], v[112:127]
	ds_read_b64_tr_b16 v[192:193], v200 offset:26624
	ds_read_b64_tr_b16 v[194:195], v200 offset:27136
	s_waitcnt lgkmcnt(13)
	v_mfma_f32_32x32x16_bf16 v[96:111], v[172:175], v[148:151], v[96:111]
	v_add_f32_e32 v80, v66, v80
	v_add_f32_e32 v80, v67, v80
	v_add_f32_e32 v80, v68, v80
	v_add_f32_e32 v80, v69, v80
	v_cvt_pk_bf16_f32 v132, v64, v65
	v_cvt_pk_bf16_f32 v133, v66, v67
	ds_read_b64_tr_b16 v[172:173], v200 offset:30720
	ds_read_b64_tr_b16 v[174:175], v200 offset:31232
	v_add_f32_e32 v64, v70, v80
	v_add_f32_e32 v64, v71, v64
	v_add_f32_e32 v64, v72, v64
	v_add_f32_e32 v64, v73, v64
	v_cvt_pk_bf16_f32 v134, v68, v69
	v_cvt_pk_bf16_f32 v135, v70, v71
	s_waitcnt lgkmcnt(14)
	v_mfma_f32_32x32x16_bf16 v[112:127], v[168:171], v[148:151], v[112:127]
	ds_read_b64_tr_b16 v[168:169], v200 offset:27648
	ds_read_b64_tr_b16 v[170:171], v200 offset:28160
	s_waitcnt lgkmcnt(14)
	v_mfma_f32_32x32x16_bf16 v[96:111], v[164:167], v[144:147], v[96:111]
	v_add_f32_e32 v64, v74, v64
	v_add_f32_e32 v64, v75, v64
	v_add_f32_e32 v64, v76, v64
	v_add_f32_e32 v64, v77, v64
	v_cvt_pk_bf16_f32 v128, v72, v73
	v_cvt_pk_bf16_f32 v129, v74, v75
	ds_read_b64_tr_b16 v[176:177], v200 offset:31744
	ds_read_b64_tr_b16 v[178:179], v200 offset:32256
	v_add_f32_e32 v64, v78, v64
	v_mfma_f32_32x32x16_bf16 v[112:127], v[160:163], v[144:147], v[112:127]
	v_add_f32_e32 v160, v79, v64
	v_cvt_pk_bf16_f32 v130, v76, v77
	v_cvt_pk_bf16_f32 v131, v78, v79
	s_setprio 0
	v_lshl_add_u64 v[64:65], v[230:231], 0, s[64:65]
	s_add_i32 s0, s23, s26
	s_mov_b32 s1, m0
	s_mov_b32 m0, s0
	s_nop 0
	global_load_lds_dwordx4 v[64:65], off
	s_mov_b32 m0, s1
	v_lshl_add_u64 v[64:65], v[228:229], 0, s[64:65]
	s_lshl_b32 s0, s22, 1
	s_add_i32 s0, s0, s27
	s_mov_b32 s1, m0
	s_mov_b32 m0, s0
	s_nop 0
	global_load_lds_dwordx4 v[64:65], off
	s_mov_b32 m0, s1
	v_lshl_add_u64 v[64:65], v[206:207], 0, s[64:65]
	s_addk_i32 s0, 0x2000
	s_mov_b32 s1, m0
	s_mov_b32 m0, s0
	s_nop 0
	global_load_lds_dwordx4 v[64:65], off
	s_mov_b32 m0, s1
	v_max_f32_e32 v80, v96, v97
	v_max3_f32 v81, v98, v99, v113
	v_max3_f32 v80, v80, v112, v114
	v_max3_f32 v80, v80, v115, v100
	v_max3_f32 v81, v81, v102, v103
	v_max3_f32 v80, v80, v101, v116
	v_max3_f32 v81, v81, v118, v119
	v_max3_f32 v80, v80, v117, v104
	v_max3_f32 v81, v81, v106, v107
	v_max3_f32 v80, v80, v105, v120
	v_max3_f32 v81, v81, v122, v123
	v_max3_f32 v80, v80, v121, v108
	v_max3_f32 v81, v81, v110, v111
	v_max3_f32 v80, v80, v109, v124
	v_max3_f32 v81, v81, v126, v127
	v_max3_f32 v80, v80, v125, v81
	v_mov_b32_e32 v81, v80
	s_nop 1
	v_permlane32_swap_b32_e32 v80, v81
	v_max_f32_e32 v80, v80, v81
	v_cmp_lt_f32_e32 vcc, s56, v80
	s_cmp_lg_u64 vcc, 0
	v_add_f32_e32 v215, v215, v160
	s_cselect_b64 s[0:1], -1, 0
	s_cbranch_vccnz .LBB0_850

.LBB0_845:
	s_add_i32 s0, s22, 0x2000
	s_cmpk_lg_i32 s22, 0x4000
	s_cselect_b32 s24, s0, 0
	s_lshl_b32 s0, s23, 1
	v_add_u32_e32 v255, s0, v211
	s_setprio 1
	ds_read_b64_tr_b16 v[200:201], v255 offset:24576
	ds_read_b64_tr_b16 v[202:203], v255 offset:25088
	v_add_f32_e32 v100, v80, v81
	v_add_f32_e32 v100, v82, v100
	v_add_f32_e32 v100, v83, v100
	v_add_f32_e32 v100, v84, v100
	v_add_f32_e32 v116, v85, v100
	v_mfma_f32_32x32x16_bf16 v[96:111], v[96:99], v[156:159], v[236:251]
	v_cvt_pk_bf16_f32 v140, v80, v81
	v_cvt_pk_bf16_f32 v141, v82, v83
	ds_read_b64_tr_b16 v[176:177], v255 offset:28672
	ds_read_b64_tr_b16 v[178:179], v255 offset:29184
	v_add_f32_e32 v80, v86, v116
	v_add_f32_e32 v80, v87, v80
	v_add_f32_e32 v80, v88, v80
	v_add_f32_e32 v80, v89, v80
	v_cvt_pk_bf16_f32 v142, v84, v85
	v_cvt_pk_bf16_f32 v143, v86, v87
	v_mfma_f32_32x32x16_bf16 v[112:127], v[112:115], v[156:159], v[236:251]
	ds_read_b64_tr_b16 v[168:169], v255 offset:25600
	ds_read_b64_tr_b16 v[170:171], v255 offset:26112
	v_mfma_f32_32x32x16_bf16 v[96:111], v[196:199], v[152:155], v[96:111]
	v_add_f32_e32 v80, v90, v80
	v_add_f32_e32 v80, v91, v80
	v_add_f32_e32 v80, v92, v80
	v_add_f32_e32 v80, v93, v80
	v_cvt_pk_bf16_f32 v136, v88, v89
	v_cvt_pk_bf16_f32 v137, v90, v91
	ds_read_b64_tr_b16 v[172:173], v255 offset:29696
	ds_read_b64_tr_b16 v[174:175], v255 offset:30208
	v_add_f32_e32 v80, v94, v80
	v_add_f32_e32 v80, v95, v80
	v_add_f32_e32 v80, v64, v80
	v_add_f32_e32 v80, v65, v80
	v_cvt_pk_bf16_f32 v138, v92, v93
	v_cvt_pk_bf16_f32 v139, v94, v95
	v_mfma_f32_32x32x16_bf16 v[112:127], v[188:191], v[152:155], v[112:127]
	ds_read_b64_tr_b16 v[196:197], v255 offset:26624
	ds_read_b64_tr_b16 v[198:199], v255 offset:27136
	v_mfma_f32_32x32x16_bf16 v[96:111], v[184:187], v[148:151], v[96:111]
	v_add_f32_e32 v80, v66, v80
	v_add_f32_e32 v80, v67, v80
	v_add_f32_e32 v80, v68, v80
	v_add_f32_e32 v80, v69, v80
	v_cvt_pk_bf16_f32 v132, v64, v65
	v_cvt_pk_bf16_f32 v133, v66, v67
	ds_read_b64_tr_b16 v[184:185], v255 offset:30720
	ds_read_b64_tr_b16 v[186:187], v255 offset:31232
	v_add_f32_e32 v64, v70, v80
	v_add_f32_e32 v64, v71, v64
	v_add_f32_e32 v64, v72, v64
	v_add_f32_e32 v64, v73, v64
	v_cvt_pk_bf16_f32 v134, v68, v69
	v_cvt_pk_bf16_f32 v135, v70, v71
	v_mfma_f32_32x32x16_bf16 v[112:127], v[164:167], v[148:151], v[112:127]
	ds_read_b64_tr_b16 v[188:189], v255 offset:27648
	ds_read_b64_tr_b16 v[190:191], v255 offset:28160
	v_mfma_f32_32x32x16_bf16 v[96:111], v[180:183], v[144:147], v[96:111]
	v_add_f32_e32 v64, v74, v64
	v_add_f32_e32 v64, v75, v64
	v_add_f32_e32 v64, v76, v64
	v_add_f32_e32 v64, v77, v64
	v_cvt_pk_bf16_f32 v128, v72, v73
	v_cvt_pk_bf16_f32 v129, v74, v75
	ds_read_b64_tr_b16 v[192:193], v255 offset:31744
	ds_read_b64_tr_b16 v[194:195], v255 offset:32256
	v_add_f32_e32 v64, v78, v64
	v_mfma_f32_32x32x16_bf16 v[112:127], v[160:163], v[144:147], v[112:127]
	v_add_f32_e32 v160, v79, v64
	v_cvt_pk_bf16_f32 v130, v76, v77
	v_cvt_pk_bf16_f32 v131, v78, v79
	s_setprio 0
	s_add_i32 s0, s22, s26
	s_mov_b32 s1, m0
	s_mov_b32 m0, s0
	s_nop 0
	global_load_lds_dwordx4 v[230:231], off
	s_mov_b32 m0, s1
	s_lshl_b32 s0, s24, 1
	s_add_i32 s0, s0, s27
	s_mov_b32 s1, m0
	s_mov_b32 m0, s0
	s_nop 0
	global_load_lds_dwordx4 v[228:229], off
	s_mov_b32 m0, s1
	s_addk_i32 s0, 0x2000
	s_mov_b32 s1, m0
	s_mov_b32 m0, s0
	s_nop 0
	global_load_lds_dwordx4 v[206:207], off
	s_mov_b32 m0, s1
	v_max_f32_e32 v80, v96, v97
	v_max3_f32 v81, v98, v99, v113
	v_max3_f32 v80, v80, v112, v114
	v_max3_f32 v80, v80, v115, v100
	v_max3_f32 v81, v81, v102, v103
	v_max3_f32 v80, v80, v101, v116
	v_max3_f32 v81, v81, v118, v119
	v_max3_f32 v80, v80, v117, v104
	v_max3_f32 v81, v81, v106, v107
	v_max3_f32 v80, v80, v105, v120
	v_max3_f32 v81, v81, v122, v123
	v_max3_f32 v80, v80, v121, v108
	v_max3_f32 v81, v81, v110, v111
	v_max3_f32 v80, v80, v109, v124
	v_max3_f32 v81, v81, v126, v127
	v_max3_f32 v80, v80, v125, v81
	v_mov_b32_e32 v81, v80
	s_nop 1
	v_permlane32_swap_b32_e32 v80, v81
	v_max_f32_e32 v80, v80, v81
	v_cmp_lt_f32_e32 vcc, s56, v80
	s_cmp_lg_u64 vcc, 0
	v_add_f32_e32 v215, v215, v160
	s_cselect_b64 s[0:1], -1, 0
	s_cbranch_vccnz .LBB0_853
